# dprep: the three causal-conv history rows fetched together (six masked candidate loads, one wait) instead of three serialized round trips
# speedup vs baseline: 1.0069x; 1.0069x over previous
.LBB0_782:
	s_andn2_saveexec_b64 s[40:41], s[40:41]
	s_cbranch_execz .LBB0_819
	v_readlane_b32 s56, v252, 3
	v_ashrrev_i32_e32 v3, 31, v2
	v_readlane_b32 s66, v252, 13
	v_readlane_b32 s67, v252, 14
	v_lshl_add_u64 v[2:3], s[22:23], 0, v[2:3]
	s_movk_i32 s5, 0x4800
	v_mov_b64_e32 v[6:7], s[66:67]
	v_lshl_or_b32 v12, v5, 7, v122
	v_mad_u64_u32 v[10:11], s[44:45], v2, s5, v[6:7]
	v_ashrrev_i32_e32 v13, 31, v12
	v_mad_i32_i24 v11, v3, s5, v11
	v_lshl_add_u64 v[2:3], v[12:13], 2, s[20:21]
	v_add_co_u32_e32 v6, vcc, 0x1000, v2
	global_load_dwordx2 v[98:99], v[2:3], off
	s_nop 0
	v_addc_co_u32_e32 v7, vcc, 0, v3, vcc
	global_load_dwordx2 v[100:101], v[6:7], off offset:2048
	v_add_co_u32_e32 v6, vcc, 0x3000, v2
	v_add_u32_e32 v14, v9, v123
	s_nop 0
	v_addc_co_u32_e32 v7, vcc, 0, v3, vcc
	global_load_dwordx2 v[102:103], v[6:7], off
	v_add_co_u32_e32 v2, vcc, 0x4000, v2
	v_readlane_b32 s57, v252, 4
	s_nop 0
	v_addc_co_u32_e32 v3, vcc, 0, v3, vcc
	global_load_dwordx2 v[104:105], v[2:3], off offset:2048
	v_cmp_gt_i32_e32 vcc, 3, v14
	v_readlane_b32 s58, v252, 5
	v_readlane_b32 s59, v252, 6
	v_readlane_b32 s60, v252, 7
	v_readlane_b32 s61, v252, 8
	v_readlane_b32 s62, v252, 9
	v_readlane_b32 s63, v252, 10
	v_readlane_b32 s64, v252, 11
	v_readlane_b32 s65, v252, 12
	v_readlane_b32 s68, v252, 15
	v_readlane_b32 s69, v252, 16
	v_readlane_b32 s70, v252, 17
	v_readlane_b32 s71, v252, 18
	v_lshl_add_u64 v[106:107], v[12:13], 1, s[24:25]
	s_mov_b64 s[44:45], exec
	s_movk_i32 s11, 0x600
	s_movk_i32 s5, 0xc00
	v_mul_lo_u32 v206, v14, s11
	v_cmp_gt_i32_e32 vcc, 3, v14
	s_and_b64 s[56:57], vcc, s[2:3]
	s_and_b64 s[56:57], s[56:57], s[44:45]
	s_andn2_b64 s[64:65], s[44:45], vcc
	s_mov_b64 exec, s[56:57]
	v_add_u32_e32 v194, v12, v206
	v_ashrrev_i32_e32 v195, 31, v194
	v_lshl_add_u64 v[194:195], v[194:195], 2, v[10:11]
	global_load_dwordx2 v[108:109], v[194:195], off
	s_mov_b64 exec, s[64:65]
	v_add3_u32 v200, v14, v0, -3
	v_mad_i64_i32 v[200:201], s[70:71], v200, s5, v[106:107]
	global_load_dword v114, v[200:201], off
	s_mov_b64 exec, s[44:45]
	v_cmp_gt_i32_e32 vcc, 2, v14
	s_and_b64 s[58:59], vcc, s[2:3]
	s_and_b64 s[58:59], s[58:59], s[44:45]
	s_andn2_b64 s[66:67], s[44:45], vcc
	s_mov_b64 exec, s[58:59]
	v_add3_u32 v196, v12, v206, s11
	v_ashrrev_i32_e32 v197, 31, v196
	v_lshl_add_u64 v[196:197], v[196:197], 2, v[10:11]
	global_load_dwordx2 v[110:111], v[196:197], off
	s_mov_b64 exec, s[66:67]
	v_add3_u32 v202, v14, v0, -2
	v_mad_i64_i32 v[202:203], s[70:71], v202, s5, v[106:107]
	global_load_dword v115, v[202:203], off
	s_mov_b64 exec, s[44:45]
	v_cmp_gt_i32_e32 vcc, 1, v14
	s_and_b64 s[62:63], vcc, s[2:3]
	s_and_b64 s[62:63], s[62:63], s[44:45]
	s_andn2_b64 s[68:69], s[44:45], vcc
	s_mov_b64 exec, s[62:63]
	v_add3_u32 v198, v12, v206, s5
	v_ashrrev_i32_e32 v199, 31, v198
	v_lshl_add_u64 v[198:199], v[198:199], 2, v[10:11]
	global_load_dwordx2 v[112:113], v[198:199], off
	s_mov_b64 exec, s[68:69]
	v_add3_u32 v204, v14, v0, -1
	v_mad_i64_i32 v[204:205], s[70:71], v204, s5, v[106:107]
	global_load_dword v116, v[204:205], off
	s_mov_b64 exec, s[44:45]
	s_waitcnt vmcnt(0)
	v_lshlrev_b32_e32 v206, 16, v114
	v_and_b32_e32 v207, 0xffff0000, v114
	v_cndmask_b32_e64 v2, 0, v206, s[64:65]
	v_cndmask_b32_e64 v6, 0, v207, s[64:65]
	v_cndmask_b32_e64 v2, v2, v108, s[56:57]
	v_cndmask_b32_e64 v6, v6, v109, s[56:57]
	v_lshlrev_b32_e32 v206, 16, v115
	v_and_b32_e32 v207, 0xffff0000, v115
	v_cndmask_b32_e64 v3, 0, v206, s[66:67]
	v_cndmask_b32_e64 v7, 0, v207, s[66:67]
	v_cndmask_b32_e64 v3, v3, v110, s[58:59]
	v_cndmask_b32_e64 v7, v7, v111, s[58:59]
	v_lshlrev_b32_e32 v206, 16, v116
	v_and_b32_e32 v207, 0xffff0000, v116
	v_cndmask_b32_e64 v4, 0, v206, s[68:69]
	v_cndmask_b32_e64 v8, 0, v207, s[68:69]
	v_cndmask_b32_e64 v4, v4, v112, s[62:63]
	v_cndmask_b32_e64 v8, v8, v113, s[62:63]
	v_add3_u32 v0, v123, v0, v9
	s_mov_b32 s44, 0
	v_mov_b32_e32 v9, v179
	v_readfirstlane_b32 s58, v186
	v_readfirstlane_b32 s59, v123
	s_sub_i32 s58, s58, s59
	s_max_i32 s58, s58, 0
	s_min_i32 s58, s58, 32
	s_movk_i32 s56, 0xc00
	s_mov_b32 s57, 0
	s_movk_i32 s11, 0xc00
	v_mad_i64_i32 v[10:11], s[48:49], v0, s11, v[106:107]
	global_load_dword v194, v[10:11], off
	v_lshl_add_u64 v[10:11], v[10:11], 0, s[56:57]
	global_load_dword v195, v[10:11], off
	v_lshl_add_u64 v[10:11], v[10:11], 0, s[56:57]
	global_load_dword v196, v[10:11], off
	v_lshl_add_u64 v[10:11], v[10:11], 0, s[56:57]
	global_load_dword v197, v[10:11], off
	v_lshl_add_u64 v[10:11], v[10:11], 0, s[56:57]
	global_load_dword v198, v[10:11], off
	v_lshl_add_u64 v[10:11], v[10:11], 0, s[56:57]
	global_load_dword v199, v[10:11], off
	v_lshl_add_u64 v[10:11], v[10:11], 0, s[56:57]
	global_load_dword v200, v[10:11], off
	v_lshl_add_u64 v[10:11], v[10:11], 0, s[56:57]
	global_load_dword v201, v[10:11], off
	v_lshl_add_u64 v[10:11], v[10:11], 0, s[56:57]
	global_load_dword v202, v[10:11], off
	v_lshl_add_u64 v[10:11], v[10:11], 0, s[56:57]
	global_load_dword v203, v[10:11], off
	v_lshl_add_u64 v[10:11], v[10:11], 0, s[56:57]
	global_load_dword v204, v[10:11], off
	v_lshl_add_u64 v[10:11], v[10:11], 0, s[56:57]
	global_load_dword v205, v[10:11], off
	v_lshl_add_u64 v[10:11], v[10:11], 0, s[56:57]
	global_load_dword v206, v[10:11], off
	v_lshl_add_u64 v[10:11], v[10:11], 0, s[56:57]
	global_load_dword v207, v[10:11], off
	v_lshl_add_u64 v[10:11], v[10:11], 0, s[56:57]
	global_load_dword v208, v[10:11], off
	v_lshl_add_u64 v[10:11], v[10:11], 0, s[56:57]
	global_load_dword v209, v[10:11], off
	v_lshl_add_u64 v[10:11], v[10:11], 0, s[56:57]
	global_load_dword v210, v[10:11], off
	v_lshl_add_u64 v[10:11], v[10:11], 0, s[56:57]
	global_load_dword v226, v[10:11], off
	v_lshl_add_u64 v[10:11], v[10:11], 0, s[56:57]
	global_load_dword v227, v[10:11], off
	v_lshl_add_u64 v[10:11], v[10:11], 0, s[56:57]
	global_load_dword v228, v[10:11], off
	v_lshl_add_u64 v[10:11], v[10:11], 0, s[56:57]
	global_load_dword v229, v[10:11], off
	v_lshl_add_u64 v[10:11], v[10:11], 0, s[56:57]
	global_load_dword v230, v[10:11], off
	v_lshl_add_u64 v[10:11], v[10:11], 0, s[56:57]
	global_load_dword v231, v[10:11], off
	v_lshl_add_u64 v[10:11], v[10:11], 0, s[56:57]
	global_load_dword v232, v[10:11], off
	v_lshl_add_u64 v[10:11], v[10:11], 0, s[56:57]
	global_load_dword v233, v[10:11], off
	v_lshl_add_u64 v[10:11], v[10:11], 0, s[56:57]
	global_load_dword v234, v[10:11], off
	v_lshl_add_u64 v[10:11], v[10:11], 0, s[56:57]
	global_load_dword v235, v[10:11], off
	v_lshl_add_u64 v[10:11], v[10:11], 0, s[56:57]
	global_load_dword v236, v[10:11], off
	v_lshl_add_u64 v[10:11], v[10:11], 0, s[56:57]
	global_load_dword v237, v[10:11], off
	v_lshl_add_u64 v[10:11], v[10:11], 0, s[56:57]
	global_load_dword v238, v[10:11], off
	v_lshl_add_u64 v[10:11], v[10:11], 0, s[56:57]
	global_load_dword v239, v[10:11], off
	v_lshl_add_u64 v[10:11], v[10:11], 0, s[56:57]
	global_load_dword v240, v[10:11], off
	v_lshl_add_u64 v[10:11], v[10:11], 0, s[56:57]
	v_mov_b32_e32 v14, v2
	v_mov_b32_e32 v15, v6
	v_mov_b32_e32 v16, v3
	v_mov_b32_e32 v17, v7
	v_mov_b32_e32 v108, v4
	v_mov_b32_e32 v109, v8
	s_waitcnt vmcnt(31)
	v_lshlrev_b32_e32 v110, 16, v194
	v_and_b32_e32 v111, 0xffff0000, v194
	v_pk_mul_f32 v[112:113], v[100:101], v[16:17]
	v_pk_fma_f32 v[112:113], v[98:99], v[14:15], v[112:113]
	v_pk_fma_f32 v[112:113], v[102:103], v[108:109], v[112:113]
	v_pk_fma_f32 v[112:113], v[104:105], v[110:111], v[112:113]
	s_cmp_gt_u32 s58, 0
	s_cselect_b32 s60, -1, 0
	v_mul_f32_e32 v114, 0xbfb8aa3b, v112
	v_mul_f32_e32 v115, 0xbfb8aa3b, v113
	v_exp_f32_e32 v114, v114
	v_exp_f32_e32 v115, v115
	s_nop 0
	v_add_f32_e32 v114, 1.0, v114
	v_add_f32_e32 v115, 1.0, v115
	v_rcp_f32_e32 v114, v114
	v_rcp_f32_e32 v115, v115
	s_nop 0
	v_pk_mul_f32 v[114:115], v[112:113], v[114:115]
	v_and_b32_e32 v114, s60, v114
	v_and_b32_e32 v115, s60, v115
	ds_write_b64 v9, v[114:115] offset:0
	s_waitcnt vmcnt(30)
	v_lshlrev_b32_e32 v14, 16, v195
	v_and_b32_e32 v15, 0xffff0000, v195
	v_pk_mul_f32 v[112:113], v[100:101], v[108:109]
	v_pk_fma_f32 v[112:113], v[98:99], v[16:17], v[112:113]
	v_pk_fma_f32 v[112:113], v[102:103], v[110:111], v[112:113]
	v_pk_fma_f32 v[112:113], v[104:105], v[14:15], v[112:113]
	s_cmp_gt_u32 s58, 1
	s_cselect_b32 s60, -1, 0
	v_mul_f32_e32 v114, 0xbfb8aa3b, v112
	v_mul_f32_e32 v115, 0xbfb8aa3b, v113
	v_exp_f32_e32 v114, v114
	v_exp_f32_e32 v115, v115
	s_nop 0
	v_add_f32_e32 v114, 1.0, v114
	v_add_f32_e32 v115, 1.0, v115
	v_rcp_f32_e32 v114, v114
	v_rcp_f32_e32 v115, v115
	s_nop 0
	v_pk_mul_f32 v[114:115], v[112:113], v[114:115]
	v_and_b32_e32 v114, s60, v114
	v_and_b32_e32 v115, s60, v115
	ds_write_b64 v9, v[114:115] offset:1552
	s_waitcnt vmcnt(29)
	v_lshlrev_b32_e32 v16, 16, v196
	v_and_b32_e32 v17, 0xffff0000, v196
	v_pk_mul_f32 v[112:113], v[100:101], v[110:111]
	v_pk_fma_f32 v[112:113], v[98:99], v[108:109], v[112:113]
	v_pk_fma_f32 v[112:113], v[102:103], v[14:15], v[112:113]
	v_pk_fma_f32 v[112:113], v[104:105], v[16:17], v[112:113]
	s_cmp_gt_u32 s58, 2
	s_cselect_b32 s60, -1, 0
	v_mul_f32_e32 v114, 0xbfb8aa3b, v112
	v_mul_f32_e32 v115, 0xbfb8aa3b, v113
	v_exp_f32_e32 v114, v114
	v_exp_f32_e32 v115, v115
	s_nop 0
	v_add_f32_e32 v114, 1.0, v114
	v_add_f32_e32 v115, 1.0, v115
	v_rcp_f32_e32 v114, v114
	v_rcp_f32_e32 v115, v115
	s_nop 0
	v_pk_mul_f32 v[114:115], v[112:113], v[114:115]
	v_and_b32_e32 v114, s60, v114
	v_and_b32_e32 v115, s60, v115
	ds_write_b64 v9, v[114:115] offset:3104
	s_waitcnt vmcnt(28)
	v_lshlrev_b32_e32 v108, 16, v197
	v_and_b32_e32 v109, 0xffff0000, v197
	v_pk_mul_f32 v[112:113], v[100:101], v[14:15]
	v_pk_fma_f32 v[112:113], v[98:99], v[110:111], v[112:113]
	v_pk_fma_f32 v[112:113], v[102:103], v[16:17], v[112:113]
	v_pk_fma_f32 v[112:113], v[104:105], v[108:109], v[112:113]
	s_cmp_gt_u32 s58, 3
	s_cselect_b32 s60, -1, 0
	v_mul_f32_e32 v114, 0xbfb8aa3b, v112
	v_mul_f32_e32 v115, 0xbfb8aa3b, v113
	v_exp_f32_e32 v114, v114
	v_exp_f32_e32 v115, v115
	s_nop 0
	v_add_f32_e32 v114, 1.0, v114
	v_add_f32_e32 v115, 1.0, v115
	v_rcp_f32_e32 v114, v114
	v_rcp_f32_e32 v115, v115
	s_nop 0
	v_pk_mul_f32 v[114:115], v[112:113], v[114:115]
	v_and_b32_e32 v114, s60, v114
	v_and_b32_e32 v115, s60, v115
	ds_write_b64 v9, v[114:115] offset:4656
	s_waitcnt vmcnt(27)
	v_lshlrev_b32_e32 v110, 16, v198
	v_and_b32_e32 v111, 0xffff0000, v198
	v_pk_mul_f32 v[112:113], v[100:101], v[16:17]
	v_pk_fma_f32 v[112:113], v[98:99], v[14:15], v[112:113]
	v_pk_fma_f32 v[112:113], v[102:103], v[108:109], v[112:113]
	v_pk_fma_f32 v[112:113], v[104:105], v[110:111], v[112:113]
	s_cmp_gt_u32 s58, 4
	s_cselect_b32 s60, -1, 0
	v_mul_f32_e32 v114, 0xbfb8aa3b, v112
	v_mul_f32_e32 v115, 0xbfb8aa3b, v113
	v_exp_f32_e32 v114, v114
	v_exp_f32_e32 v115, v115
	s_nop 0
	v_add_f32_e32 v114, 1.0, v114
	v_add_f32_e32 v115, 1.0, v115
	v_rcp_f32_e32 v114, v114
	v_rcp_f32_e32 v115, v115
	s_nop 0
	v_pk_mul_f32 v[114:115], v[112:113], v[114:115]
	v_and_b32_e32 v114, s60, v114
	v_and_b32_e32 v115, s60, v115
	ds_write_b64 v9, v[114:115] offset:6208
	s_waitcnt vmcnt(26)
	v_lshlrev_b32_e32 v14, 16, v199
	v_and_b32_e32 v15, 0xffff0000, v199
	v_pk_mul_f32 v[112:113], v[100:101], v[108:109]
	v_pk_fma_f32 v[112:113], v[98:99], v[16:17], v[112:113]
	v_pk_fma_f32 v[112:113], v[102:103], v[110:111], v[112:113]
	v_pk_fma_f32 v[112:113], v[104:105], v[14:15], v[112:113]
	s_cmp_gt_u32 s58, 5
	s_cselect_b32 s60, -1, 0
	v_mul_f32_e32 v114, 0xbfb8aa3b, v112
	v_mul_f32_e32 v115, 0xbfb8aa3b, v113
	v_exp_f32_e32 v114, v114
	v_exp_f32_e32 v115, v115
	s_nop 0
	v_add_f32_e32 v114, 1.0, v114
	v_add_f32_e32 v115, 1.0, v115
	v_rcp_f32_e32 v114, v114
	v_rcp_f32_e32 v115, v115
	s_nop 0
	v_pk_mul_f32 v[114:115], v[112:113], v[114:115]
	v_and_b32_e32 v114, s60, v114
	v_and_b32_e32 v115, s60, v115
	ds_write_b64 v9, v[114:115] offset:7760
	s_waitcnt vmcnt(25)
	v_lshlrev_b32_e32 v16, 16, v200
	v_and_b32_e32 v17, 0xffff0000, v200
	v_pk_mul_f32 v[112:113], v[100:101], v[110:111]
	v_pk_fma_f32 v[112:113], v[98:99], v[108:109], v[112:113]
	v_pk_fma_f32 v[112:113], v[102:103], v[14:15], v[112:113]
	v_pk_fma_f32 v[112:113], v[104:105], v[16:17], v[112:113]
	s_cmp_gt_u32 s58, 6
	s_cselect_b32 s60, -1, 0
	v_mul_f32_e32 v114, 0xbfb8aa3b, v112
	v_mul_f32_e32 v115, 0xbfb8aa3b, v113
	v_exp_f32_e32 v114, v114
	v_exp_f32_e32 v115, v115
	s_nop 0
	v_add_f32_e32 v114, 1.0, v114
	v_add_f32_e32 v115, 1.0, v115
	v_rcp_f32_e32 v114, v114
	v_rcp_f32_e32 v115, v115
	s_nop 0
	v_pk_mul_f32 v[114:115], v[112:113], v[114:115]
	v_and_b32_e32 v114, s60, v114
	v_and_b32_e32 v115, s60, v115
	ds_write_b64 v9, v[114:115] offset:9312
	s_waitcnt vmcnt(24)
	v_lshlrev_b32_e32 v108, 16, v201
	v_and_b32_e32 v109, 0xffff0000, v201
	v_pk_mul_f32 v[112:113], v[100:101], v[14:15]
	v_pk_fma_f32 v[112:113], v[98:99], v[110:111], v[112:113]
	v_pk_fma_f32 v[112:113], v[102:103], v[16:17], v[112:113]
	v_pk_fma_f32 v[112:113], v[104:105], v[108:109], v[112:113]
	s_cmp_gt_u32 s58, 7
	s_cselect_b32 s60, -1, 0
	v_mul_f32_e32 v114, 0xbfb8aa3b, v112
	v_mul_f32_e32 v115, 0xbfb8aa3b, v113
	v_exp_f32_e32 v114, v114
	v_exp_f32_e32 v115, v115
	s_nop 0
	v_add_f32_e32 v114, 1.0, v114
	v_add_f32_e32 v115, 1.0, v115
	v_rcp_f32_e32 v114, v114
	v_rcp_f32_e32 v115, v115
	s_nop 0
	v_pk_mul_f32 v[114:115], v[112:113], v[114:115]
	v_and_b32_e32 v114, s60, v114
	v_and_b32_e32 v115, s60, v115
	ds_write_b64 v9, v[114:115] offset:10864
	s_waitcnt vmcnt(23)
	v_lshlrev_b32_e32 v110, 16, v202
	v_and_b32_e32 v111, 0xffff0000, v202
	v_pk_mul_f32 v[112:113], v[100:101], v[16:17]
	v_pk_fma_f32 v[112:113], v[98:99], v[14:15], v[112:113]
	v_pk_fma_f32 v[112:113], v[102:103], v[108:109], v[112:113]
	v_pk_fma_f32 v[112:113], v[104:105], v[110:111], v[112:113]
	s_cmp_gt_u32 s58, 8
	s_cselect_b32 s60, -1, 0
	v_mul_f32_e32 v114, 0xbfb8aa3b, v112
	v_mul_f32_e32 v115, 0xbfb8aa3b, v113
	v_exp_f32_e32 v114, v114
	v_exp_f32_e32 v115, v115
	s_nop 0
	v_add_f32_e32 v114, 1.0, v114
	v_add_f32_e32 v115, 1.0, v115
	v_rcp_f32_e32 v114, v114
	v_rcp_f32_e32 v115, v115
	s_nop 0
	v_pk_mul_f32 v[114:115], v[112:113], v[114:115]
	v_and_b32_e32 v114, s60, v114
	v_and_b32_e32 v115, s60, v115
	ds_write_b64 v9, v[114:115] offset:12416
	s_waitcnt vmcnt(22)
	v_lshlrev_b32_e32 v14, 16, v203
	v_and_b32_e32 v15, 0xffff0000, v203
	v_pk_mul_f32 v[112:113], v[100:101], v[108:109]
	v_pk_fma_f32 v[112:113], v[98:99], v[16:17], v[112:113]
	v_pk_fma_f32 v[112:113], v[102:103], v[110:111], v[112:113]
	v_pk_fma_f32 v[112:113], v[104:105], v[14:15], v[112:113]
	s_cmp_gt_u32 s58, 9
	s_cselect_b32 s60, -1, 0
	v_mul_f32_e32 v114, 0xbfb8aa3b, v112
	v_mul_f32_e32 v115, 0xbfb8aa3b, v113
	v_exp_f32_e32 v114, v114
	v_exp_f32_e32 v115, v115
	s_nop 0
	v_add_f32_e32 v114, 1.0, v114
	v_add_f32_e32 v115, 1.0, v115
	v_rcp_f32_e32 v114, v114
	v_rcp_f32_e32 v115, v115
	s_nop 0
	v_pk_mul_f32 v[114:115], v[112:113], v[114:115]
	v_and_b32_e32 v114, s60, v114
	v_and_b32_e32 v115, s60, v115
	ds_write_b64 v9, v[114:115] offset:13968
	s_waitcnt vmcnt(21)
	v_lshlrev_b32_e32 v16, 16, v204
	v_and_b32_e32 v17, 0xffff0000, v204
	v_pk_mul_f32 v[112:113], v[100:101], v[110:111]
	v_pk_fma_f32 v[112:113], v[98:99], v[108:109], v[112:113]
	v_pk_fma_f32 v[112:113], v[102:103], v[14:15], v[112:113]
	v_pk_fma_f32 v[112:113], v[104:105], v[16:17], v[112:113]
	s_cmp_gt_u32 s58, 10
	s_cselect_b32 s60, -1, 0
	v_mul_f32_e32 v114, 0xbfb8aa3b, v112
	v_mul_f32_e32 v115, 0xbfb8aa3b, v113
	v_exp_f32_e32 v114, v114
	v_exp_f32_e32 v115, v115
	s_nop 0
	v_add_f32_e32 v114, 1.0, v114
	v_add_f32_e32 v115, 1.0, v115
	v_rcp_f32_e32 v114, v114
	v_rcp_f32_e32 v115, v115
	s_nop 0
	v_pk_mul_f32 v[114:115], v[112:113], v[114:115]
	v_and_b32_e32 v114, s60, v114
	v_and_b32_e32 v115, s60, v115
	ds_write_b64 v9, v[114:115] offset:15520
	s_waitcnt vmcnt(20)
	v_lshlrev_b32_e32 v108, 16, v205
	v_and_b32_e32 v109, 0xffff0000, v205
	v_pk_mul_f32 v[112:113], v[100:101], v[14:15]
	v_pk_fma_f32 v[112:113], v[98:99], v[110:111], v[112:113]
	v_pk_fma_f32 v[112:113], v[102:103], v[16:17], v[112:113]
	v_pk_fma_f32 v[112:113], v[104:105], v[108:109], v[112:113]
	s_cmp_gt_u32 s58, 11
	s_cselect_b32 s60, -1, 0
	v_mul_f32_e32 v114, 0xbfb8aa3b, v112
	v_mul_f32_e32 v115, 0xbfb8aa3b, v113
	v_exp_f32_e32 v114, v114
	v_exp_f32_e32 v115, v115
	s_nop 0
	v_add_f32_e32 v114, 1.0, v114
	v_add_f32_e32 v115, 1.0, v115
	v_rcp_f32_e32 v114, v114
	v_rcp_f32_e32 v115, v115
	s_nop 0
	v_pk_mul_f32 v[114:115], v[112:113], v[114:115]
	v_and_b32_e32 v114, s60, v114
	v_and_b32_e32 v115, s60, v115
	ds_write_b64 v9, v[114:115] offset:17072
	s_waitcnt vmcnt(19)
	v_lshlrev_b32_e32 v110, 16, v206
	v_and_b32_e32 v111, 0xffff0000, v206
	v_pk_mul_f32 v[112:113], v[100:101], v[16:17]
	v_pk_fma_f32 v[112:113], v[98:99], v[14:15], v[112:113]
	v_pk_fma_f32 v[112:113], v[102:103], v[108:109], v[112:113]
	v_pk_fma_f32 v[112:113], v[104:105], v[110:111], v[112:113]
	s_cmp_gt_u32 s58, 12
	s_cselect_b32 s60, -1, 0
	v_mul_f32_e32 v114, 0xbfb8aa3b, v112
	v_mul_f32_e32 v115, 0xbfb8aa3b, v113
	v_exp_f32_e32 v114, v114
	v_exp_f32_e32 v115, v115
	s_nop 0
	v_add_f32_e32 v114, 1.0, v114
	v_add_f32_e32 v115, 1.0, v115
	v_rcp_f32_e32 v114, v114
	v_rcp_f32_e32 v115, v115
	s_nop 0
	v_pk_mul_f32 v[114:115], v[112:113], v[114:115]
	v_and_b32_e32 v114, s60, v114
	v_and_b32_e32 v115, s60, v115
	ds_write_b64 v9, v[114:115] offset:18624
	s_waitcnt vmcnt(18)
	v_lshlrev_b32_e32 v14, 16, v207
	v_and_b32_e32 v15, 0xffff0000, v207
	v_pk_mul_f32 v[112:113], v[100:101], v[108:109]
	v_pk_fma_f32 v[112:113], v[98:99], v[16:17], v[112:113]
	v_pk_fma_f32 v[112:113], v[102:103], v[110:111], v[112:113]
	v_pk_fma_f32 v[112:113], v[104:105], v[14:15], v[112:113]
	s_cmp_gt_u32 s58, 13
	s_cselect_b32 s60, -1, 0
	v_mul_f32_e32 v114, 0xbfb8aa3b, v112
	v_mul_f32_e32 v115, 0xbfb8aa3b, v113
	v_exp_f32_e32 v114, v114
	v_exp_f32_e32 v115, v115
	s_nop 0
	v_add_f32_e32 v114, 1.0, v114
	v_add_f32_e32 v115, 1.0, v115
	v_rcp_f32_e32 v114, v114
	v_rcp_f32_e32 v115, v115
	s_nop 0
	v_pk_mul_f32 v[114:115], v[112:113], v[114:115]
	v_and_b32_e32 v114, s60, v114
	v_and_b32_e32 v115, s60, v115
	ds_write_b64 v9, v[114:115] offset:20176
	s_waitcnt vmcnt(17)
	v_lshlrev_b32_e32 v16, 16, v208
	v_and_b32_e32 v17, 0xffff0000, v208
	v_pk_mul_f32 v[112:113], v[100:101], v[110:111]
	v_pk_fma_f32 v[112:113], v[98:99], v[108:109], v[112:113]
	v_pk_fma_f32 v[112:113], v[102:103], v[14:15], v[112:113]
	v_pk_fma_f32 v[112:113], v[104:105], v[16:17], v[112:113]
	s_cmp_gt_u32 s58, 14
	s_cselect_b32 s60, -1, 0
	v_mul_f32_e32 v114, 0xbfb8aa3b, v112
	v_mul_f32_e32 v115, 0xbfb8aa3b, v113
	v_exp_f32_e32 v114, v114
	v_exp_f32_e32 v115, v115
	s_nop 0
	v_add_f32_e32 v114, 1.0, v114
	v_add_f32_e32 v115, 1.0, v115
	v_rcp_f32_e32 v114, v114
	v_rcp_f32_e32 v115, v115
	s_nop 0
	v_pk_mul_f32 v[114:115], v[112:113], v[114:115]
	v_and_b32_e32 v114, s60, v114
	v_and_b32_e32 v115, s60, v115
	ds_write_b64 v9, v[114:115] offset:21728
	s_waitcnt vmcnt(16)
	v_lshlrev_b32_e32 v108, 16, v209
	v_and_b32_e32 v109, 0xffff0000, v209
	v_pk_mul_f32 v[112:113], v[100:101], v[14:15]
	v_pk_fma_f32 v[112:113], v[98:99], v[110:111], v[112:113]
	v_pk_fma_f32 v[112:113], v[102:103], v[16:17], v[112:113]
	v_pk_fma_f32 v[112:113], v[104:105], v[108:109], v[112:113]
	s_cmp_gt_u32 s58, 15
	s_cselect_b32 s60, -1, 0
	v_mul_f32_e32 v114, 0xbfb8aa3b, v112
	v_mul_f32_e32 v115, 0xbfb8aa3b, v113
	v_exp_f32_e32 v114, v114
	v_exp_f32_e32 v115, v115
	s_nop 0
	v_add_f32_e32 v114, 1.0, v114
	v_add_f32_e32 v115, 1.0, v115
	v_rcp_f32_e32 v114, v114
	v_rcp_f32_e32 v115, v115
	s_nop 0
	v_pk_mul_f32 v[114:115], v[112:113], v[114:115]
	v_and_b32_e32 v114, s60, v114
	v_and_b32_e32 v115, s60, v115
	ds_write_b64 v9, v[114:115] offset:23280
	s_waitcnt vmcnt(15)
	v_lshlrev_b32_e32 v110, 16, v210
	v_and_b32_e32 v111, 0xffff0000, v210
	v_pk_mul_f32 v[112:113], v[100:101], v[16:17]
	v_pk_fma_f32 v[112:113], v[98:99], v[14:15], v[112:113]
	v_pk_fma_f32 v[112:113], v[102:103], v[108:109], v[112:113]
	v_pk_fma_f32 v[112:113], v[104:105], v[110:111], v[112:113]
	s_cmp_gt_u32 s58, 16
	s_cselect_b32 s60, -1, 0
	v_mul_f32_e32 v114, 0xbfb8aa3b, v112
	v_mul_f32_e32 v115, 0xbfb8aa3b, v113
	v_exp_f32_e32 v114, v114
	v_exp_f32_e32 v115, v115
	s_nop 0
	v_add_f32_e32 v114, 1.0, v114
	v_add_f32_e32 v115, 1.0, v115
	v_rcp_f32_e32 v114, v114
	v_rcp_f32_e32 v115, v115
	s_nop 0
	v_pk_mul_f32 v[114:115], v[112:113], v[114:115]
	v_and_b32_e32 v114, s60, v114
	v_and_b32_e32 v115, s60, v115
	ds_write_b64 v9, v[114:115] offset:24832
	s_waitcnt vmcnt(14)
	v_lshlrev_b32_e32 v14, 16, v226
	v_and_b32_e32 v15, 0xffff0000, v226
	v_pk_mul_f32 v[112:113], v[100:101], v[108:109]
	v_pk_fma_f32 v[112:113], v[98:99], v[16:17], v[112:113]
	v_pk_fma_f32 v[112:113], v[102:103], v[110:111], v[112:113]
	v_pk_fma_f32 v[112:113], v[104:105], v[14:15], v[112:113]
	s_cmp_gt_u32 s58, 17
	s_cselect_b32 s60, -1, 0
	v_mul_f32_e32 v114, 0xbfb8aa3b, v112
	v_mul_f32_e32 v115, 0xbfb8aa3b, v113
	v_exp_f32_e32 v114, v114
	v_exp_f32_e32 v115, v115
	s_nop 0
	v_add_f32_e32 v114, 1.0, v114
	v_add_f32_e32 v115, 1.0, v115
	v_rcp_f32_e32 v114, v114
	v_rcp_f32_e32 v115, v115
	s_nop 0
	v_pk_mul_f32 v[114:115], v[112:113], v[114:115]
	v_and_b32_e32 v114, s60, v114
	v_and_b32_e32 v115, s60, v115
	ds_write_b64 v9, v[114:115] offset:26384
	s_waitcnt vmcnt(13)
	v_lshlrev_b32_e32 v16, 16, v227
	v_and_b32_e32 v17, 0xffff0000, v227
	v_pk_mul_f32 v[112:113], v[100:101], v[110:111]
	v_pk_fma_f32 v[112:113], v[98:99], v[108:109], v[112:113]
	v_pk_fma_f32 v[112:113], v[102:103], v[14:15], v[112:113]
	v_pk_fma_f32 v[112:113], v[104:105], v[16:17], v[112:113]
	s_cmp_gt_u32 s58, 18
	s_cselect_b32 s60, -1, 0
	v_mul_f32_e32 v114, 0xbfb8aa3b, v112
	v_mul_f32_e32 v115, 0xbfb8aa3b, v113
	v_exp_f32_e32 v114, v114
	v_exp_f32_e32 v115, v115
	s_nop 0
	v_add_f32_e32 v114, 1.0, v114
	v_add_f32_e32 v115, 1.0, v115
	v_rcp_f32_e32 v114, v114
	v_rcp_f32_e32 v115, v115
	s_nop 0
	v_pk_mul_f32 v[114:115], v[112:113], v[114:115]
	v_and_b32_e32 v114, s60, v114
	v_and_b32_e32 v115, s60, v115
	ds_write_b64 v9, v[114:115] offset:27936
	s_waitcnt vmcnt(12)
	v_lshlrev_b32_e32 v108, 16, v228
	v_and_b32_e32 v109, 0xffff0000, v228
	v_pk_mul_f32 v[112:113], v[100:101], v[14:15]
	v_pk_fma_f32 v[112:113], v[98:99], v[110:111], v[112:113]
	v_pk_fma_f32 v[112:113], v[102:103], v[16:17], v[112:113]
	v_pk_fma_f32 v[112:113], v[104:105], v[108:109], v[112:113]
	s_cmp_gt_u32 s58, 19
	s_cselect_b32 s60, -1, 0
	v_mul_f32_e32 v114, 0xbfb8aa3b, v112
	v_mul_f32_e32 v115, 0xbfb8aa3b, v113
	v_exp_f32_e32 v114, v114
	v_exp_f32_e32 v115, v115
	s_nop 0
	v_add_f32_e32 v114, 1.0, v114
	v_add_f32_e32 v115, 1.0, v115
	v_rcp_f32_e32 v114, v114
	v_rcp_f32_e32 v115, v115
	s_nop 0
	v_pk_mul_f32 v[114:115], v[112:113], v[114:115]
	v_and_b32_e32 v114, s60, v114
	v_and_b32_e32 v115, s60, v115
	ds_write_b64 v9, v[114:115] offset:29488
	s_waitcnt vmcnt(11)
	v_lshlrev_b32_e32 v110, 16, v229
	v_and_b32_e32 v111, 0xffff0000, v229
	v_pk_mul_f32 v[112:113], v[100:101], v[16:17]
	v_pk_fma_f32 v[112:113], v[98:99], v[14:15], v[112:113]
	v_pk_fma_f32 v[112:113], v[102:103], v[108:109], v[112:113]
	v_pk_fma_f32 v[112:113], v[104:105], v[110:111], v[112:113]
	s_cmp_gt_u32 s58, 20
	s_cselect_b32 s60, -1, 0
	v_mul_f32_e32 v114, 0xbfb8aa3b, v112
	v_mul_f32_e32 v115, 0xbfb8aa3b, v113
	v_exp_f32_e32 v114, v114
	v_exp_f32_e32 v115, v115
	s_nop 0
	v_add_f32_e32 v114, 1.0, v114
	v_add_f32_e32 v115, 1.0, v115
	v_rcp_f32_e32 v114, v114
	v_rcp_f32_e32 v115, v115
	s_nop 0
	v_pk_mul_f32 v[114:115], v[112:113], v[114:115]
	v_and_b32_e32 v114, s60, v114
	v_and_b32_e32 v115, s60, v115
	ds_write_b64 v9, v[114:115] offset:31040
	s_waitcnt vmcnt(10)
	v_lshlrev_b32_e32 v14, 16, v230
	v_and_b32_e32 v15, 0xffff0000, v230
	v_pk_mul_f32 v[112:113], v[100:101], v[108:109]
	v_pk_fma_f32 v[112:113], v[98:99], v[16:17], v[112:113]
	v_pk_fma_f32 v[112:113], v[102:103], v[110:111], v[112:113]
	v_pk_fma_f32 v[112:113], v[104:105], v[14:15], v[112:113]
	s_cmp_gt_u32 s58, 21
	s_cselect_b32 s60, -1, 0
	v_mul_f32_e32 v114, 0xbfb8aa3b, v112
	v_mul_f32_e32 v115, 0xbfb8aa3b, v113
	v_exp_f32_e32 v114, v114
	v_exp_f32_e32 v115, v115
	s_nop 0
	v_add_f32_e32 v114, 1.0, v114
	v_add_f32_e32 v115, 1.0, v115
	v_rcp_f32_e32 v114, v114
	v_rcp_f32_e32 v115, v115
	s_nop 0
	v_pk_mul_f32 v[114:115], v[112:113], v[114:115]
	v_and_b32_e32 v114, s60, v114
	v_and_b32_e32 v115, s60, v115
	ds_write_b64 v9, v[114:115] offset:32592
	s_waitcnt vmcnt(9)
	v_lshlrev_b32_e32 v16, 16, v231
	v_and_b32_e32 v17, 0xffff0000, v231
	v_pk_mul_f32 v[112:113], v[100:101], v[110:111]
	v_pk_fma_f32 v[112:113], v[98:99], v[108:109], v[112:113]
	v_pk_fma_f32 v[112:113], v[102:103], v[14:15], v[112:113]
	v_pk_fma_f32 v[112:113], v[104:105], v[16:17], v[112:113]
	s_cmp_gt_u32 s58, 22
	s_cselect_b32 s60, -1, 0
	v_mul_f32_e32 v114, 0xbfb8aa3b, v112
	v_mul_f32_e32 v115, 0xbfb8aa3b, v113
	v_exp_f32_e32 v114, v114
	v_exp_f32_e32 v115, v115
	s_nop 0
	v_add_f32_e32 v114, 1.0, v114
	v_add_f32_e32 v115, 1.0, v115
	v_rcp_f32_e32 v114, v114
	v_rcp_f32_e32 v115, v115
	s_nop 0
	v_pk_mul_f32 v[114:115], v[112:113], v[114:115]
	v_and_b32_e32 v114, s60, v114
	v_and_b32_e32 v115, s60, v115
	ds_write_b64 v9, v[114:115] offset:34144
	s_waitcnt vmcnt(8)
	v_lshlrev_b32_e32 v108, 16, v232
	v_and_b32_e32 v109, 0xffff0000, v232
	v_pk_mul_f32 v[112:113], v[100:101], v[14:15]
	v_pk_fma_f32 v[112:113], v[98:99], v[110:111], v[112:113]
	v_pk_fma_f32 v[112:113], v[102:103], v[16:17], v[112:113]
	v_pk_fma_f32 v[112:113], v[104:105], v[108:109], v[112:113]
	s_cmp_gt_u32 s58, 23
	s_cselect_b32 s60, -1, 0
	v_mul_f32_e32 v114, 0xbfb8aa3b, v112
	v_mul_f32_e32 v115, 0xbfb8aa3b, v113
	v_exp_f32_e32 v114, v114
	v_exp_f32_e32 v115, v115
	s_nop 0
	v_add_f32_e32 v114, 1.0, v114
	v_add_f32_e32 v115, 1.0, v115
	v_rcp_f32_e32 v114, v114
	v_rcp_f32_e32 v115, v115
	s_nop 0
	v_pk_mul_f32 v[114:115], v[112:113], v[114:115]
	v_and_b32_e32 v114, s60, v114
	v_and_b32_e32 v115, s60, v115
	ds_write_b64 v9, v[114:115] offset:35696
	s_waitcnt vmcnt(7)
	v_lshlrev_b32_e32 v110, 16, v233
	v_and_b32_e32 v111, 0xffff0000, v233
	v_pk_mul_f32 v[112:113], v[100:101], v[16:17]
	v_pk_fma_f32 v[112:113], v[98:99], v[14:15], v[112:113]
	v_pk_fma_f32 v[112:113], v[102:103], v[108:109], v[112:113]
	v_pk_fma_f32 v[112:113], v[104:105], v[110:111], v[112:113]
	s_cmp_gt_u32 s58, 24
	s_cselect_b32 s60, -1, 0
	v_mul_f32_e32 v114, 0xbfb8aa3b, v112
	v_mul_f32_e32 v115, 0xbfb8aa3b, v113
	v_exp_f32_e32 v114, v114
	v_exp_f32_e32 v115, v115
	s_nop 0
	v_add_f32_e32 v114, 1.0, v114
	v_add_f32_e32 v115, 1.0, v115
	v_rcp_f32_e32 v114, v114
	v_rcp_f32_e32 v115, v115
	s_nop 0
	v_pk_mul_f32 v[114:115], v[112:113], v[114:115]
	v_and_b32_e32 v114, s60, v114
	v_and_b32_e32 v115, s60, v115
	ds_write_b64 v9, v[114:115] offset:37248
	s_waitcnt vmcnt(6)
	v_lshlrev_b32_e32 v14, 16, v234
	v_and_b32_e32 v15, 0xffff0000, v234
	v_pk_mul_f32 v[112:113], v[100:101], v[108:109]
	v_pk_fma_f32 v[112:113], v[98:99], v[16:17], v[112:113]
	v_pk_fma_f32 v[112:113], v[102:103], v[110:111], v[112:113]
	v_pk_fma_f32 v[112:113], v[104:105], v[14:15], v[112:113]
	s_cmp_gt_u32 s58, 25
	s_cselect_b32 s60, -1, 0
	v_mul_f32_e32 v114, 0xbfb8aa3b, v112
	v_mul_f32_e32 v115, 0xbfb8aa3b, v113
	v_exp_f32_e32 v114, v114
	v_exp_f32_e32 v115, v115
	s_nop 0
	v_add_f32_e32 v114, 1.0, v114
	v_add_f32_e32 v115, 1.0, v115
	v_rcp_f32_e32 v114, v114
	v_rcp_f32_e32 v115, v115
	s_nop 0
	v_pk_mul_f32 v[114:115], v[112:113], v[114:115]
	v_and_b32_e32 v114, s60, v114
	v_and_b32_e32 v115, s60, v115
	ds_write_b64 v9, v[114:115] offset:38800
	s_waitcnt vmcnt(5)
	v_lshlrev_b32_e32 v16, 16, v235
	v_and_b32_e32 v17, 0xffff0000, v235
	v_pk_mul_f32 v[112:113], v[100:101], v[110:111]
	v_pk_fma_f32 v[112:113], v[98:99], v[108:109], v[112:113]
	v_pk_fma_f32 v[112:113], v[102:103], v[14:15], v[112:113]
	v_pk_fma_f32 v[112:113], v[104:105], v[16:17], v[112:113]
	s_cmp_gt_u32 s58, 26
	s_cselect_b32 s60, -1, 0
	v_mul_f32_e32 v114, 0xbfb8aa3b, v112
	v_mul_f32_e32 v115, 0xbfb8aa3b, v113
	v_exp_f32_e32 v114, v114
	v_exp_f32_e32 v115, v115
	s_nop 0
	v_add_f32_e32 v114, 1.0, v114
	v_add_f32_e32 v115, 1.0, v115
	v_rcp_f32_e32 v114, v114
	v_rcp_f32_e32 v115, v115
	s_nop 0
	v_pk_mul_f32 v[114:115], v[112:113], v[114:115]
	v_and_b32_e32 v114, s60, v114
	v_and_b32_e32 v115, s60, v115
	ds_write_b64 v9, v[114:115] offset:40352
	s_waitcnt vmcnt(4)
	v_lshlrev_b32_e32 v108, 16, v236
	v_and_b32_e32 v109, 0xffff0000, v236
	v_pk_mul_f32 v[112:113], v[100:101], v[14:15]
	v_pk_fma_f32 v[112:113], v[98:99], v[110:111], v[112:113]
	v_pk_fma_f32 v[112:113], v[102:103], v[16:17], v[112:113]
	v_pk_fma_f32 v[112:113], v[104:105], v[108:109], v[112:113]
	s_cmp_gt_u32 s58, 27
	s_cselect_b32 s60, -1, 0
	v_mul_f32_e32 v114, 0xbfb8aa3b, v112
	v_mul_f32_e32 v115, 0xbfb8aa3b, v113
	v_exp_f32_e32 v114, v114
	v_exp_f32_e32 v115, v115
	s_nop 0
	v_add_f32_e32 v114, 1.0, v114
	v_add_f32_e32 v115, 1.0, v115
	v_rcp_f32_e32 v114, v114
	v_rcp_f32_e32 v115, v115
	s_nop 0
	v_pk_mul_f32 v[114:115], v[112:113], v[114:115]
	v_and_b32_e32 v114, s60, v114
	v_and_b32_e32 v115, s60, v115
	ds_write_b64 v9, v[114:115] offset:41904
	s_waitcnt vmcnt(3)
	v_lshlrev_b32_e32 v110, 16, v237
	v_and_b32_e32 v111, 0xffff0000, v237
	v_pk_mul_f32 v[112:113], v[100:101], v[16:17]
	v_pk_fma_f32 v[112:113], v[98:99], v[14:15], v[112:113]
	v_pk_fma_f32 v[112:113], v[102:103], v[108:109], v[112:113]
	v_pk_fma_f32 v[112:113], v[104:105], v[110:111], v[112:113]
	s_cmp_gt_u32 s58, 28
	s_cselect_b32 s60, -1, 0
	v_mul_f32_e32 v114, 0xbfb8aa3b, v112
	v_mul_f32_e32 v115, 0xbfb8aa3b, v113
	v_exp_f32_e32 v114, v114
	v_exp_f32_e32 v115, v115
	s_nop 0
	v_add_f32_e32 v114, 1.0, v114
	v_add_f32_e32 v115, 1.0, v115
	v_rcp_f32_e32 v114, v114
	v_rcp_f32_e32 v115, v115
	s_nop 0
	v_pk_mul_f32 v[114:115], v[112:113], v[114:115]
	v_and_b32_e32 v114, s60, v114
	v_and_b32_e32 v115, s60, v115
	ds_write_b64 v9, v[114:115] offset:43456
	s_waitcnt vmcnt(2)
	v_lshlrev_b32_e32 v14, 16, v238
	v_and_b32_e32 v15, 0xffff0000, v238
	v_pk_mul_f32 v[112:113], v[100:101], v[108:109]
	v_pk_fma_f32 v[112:113], v[98:99], v[16:17], v[112:113]
	v_pk_fma_f32 v[112:113], v[102:103], v[110:111], v[112:113]
	v_pk_fma_f32 v[112:113], v[104:105], v[14:15], v[112:113]
	s_cmp_gt_u32 s58, 29
	s_cselect_b32 s60, -1, 0
	v_mul_f32_e32 v114, 0xbfb8aa3b, v112
	v_mul_f32_e32 v115, 0xbfb8aa3b, v113
	v_exp_f32_e32 v114, v114
	v_exp_f32_e32 v115, v115
	s_nop 0
	v_add_f32_e32 v114, 1.0, v114
	v_add_f32_e32 v115, 1.0, v115
	v_rcp_f32_e32 v114, v114
	v_rcp_f32_e32 v115, v115
	s_nop 0
	v_pk_mul_f32 v[114:115], v[112:113], v[114:115]
	v_and_b32_e32 v114, s60, v114
	v_and_b32_e32 v115, s60, v115
	ds_write_b64 v9, v[114:115] offset:45008
	s_waitcnt vmcnt(1)
	v_lshlrev_b32_e32 v16, 16, v239
	v_and_b32_e32 v17, 0xffff0000, v239
	v_pk_mul_f32 v[112:113], v[100:101], v[110:111]
	v_pk_fma_f32 v[112:113], v[98:99], v[108:109], v[112:113]
	v_pk_fma_f32 v[112:113], v[102:103], v[14:15], v[112:113]
	v_pk_fma_f32 v[112:113], v[104:105], v[16:17], v[112:113]
	s_cmp_gt_u32 s58, 30
	s_cselect_b32 s60, -1, 0
	v_mul_f32_e32 v114, 0xbfb8aa3b, v112
	v_mul_f32_e32 v115, 0xbfb8aa3b, v113
	v_exp_f32_e32 v114, v114
	v_exp_f32_e32 v115, v115
	s_nop 0
	v_add_f32_e32 v114, 1.0, v114
	v_add_f32_e32 v115, 1.0, v115
	v_rcp_f32_e32 v114, v114
	v_rcp_f32_e32 v115, v115
	s_nop 0
	v_pk_mul_f32 v[114:115], v[112:113], v[114:115]
	v_and_b32_e32 v114, s60, v114
	v_and_b32_e32 v115, s60, v115
	ds_write_b64 v9, v[114:115] offset:46560
	s_waitcnt vmcnt(0)
	v_lshlrev_b32_e32 v108, 16, v240
	v_and_b32_e32 v109, 0xffff0000, v240
	v_pk_mul_f32 v[112:113], v[100:101], v[14:15]
	v_pk_fma_f32 v[112:113], v[98:99], v[110:111], v[112:113]
	v_pk_fma_f32 v[112:113], v[102:103], v[16:17], v[112:113]
	v_pk_fma_f32 v[112:113], v[104:105], v[108:109], v[112:113]
	s_cmp_gt_u32 s58, 31
	s_cselect_b32 s60, -1, 0
	v_mul_f32_e32 v114, 0xbfb8aa3b, v112
	v_mul_f32_e32 v115, 0xbfb8aa3b, v113
	v_exp_f32_e32 v114, v114
	v_exp_f32_e32 v115, v115
	s_nop 0
	v_add_f32_e32 v114, 1.0, v114
	v_add_f32_e32 v115, 1.0, v115
	v_rcp_f32_e32 v114, v114
	v_rcp_f32_e32 v115, v115
	s_nop 0
	v_pk_mul_f32 v[114:115], v[112:113], v[114:115]
	v_and_b32_e32 v114, s60, v114
	v_and_b32_e32 v115, s60, v115
	ds_write_b64 v9, v[114:115] offset:48112
	s_branch .LBB0_819
